# v30 + attention K/V tiles double-buffered in LDS: one workgroup barrier per key tile instead of two
# baseline (speedup 1.0000x reference)
; #define LAS __attribute__((address_space(3)))
; DI void u_attn2(Frame& F, int h, int qb, int sp, int ntile) {
;     ...
;     for (int t = 0; t < ntile; ++t) {
;         const int kt = kt0 + t;
;         __syncthreads();
; #pragma unroll
;         for (int i = 0; i < 3; ++i) { const int p = tid + 512 * i, r = p / 24, cc = p - r * 24; *(LAS u32x4*)(Ks + r * 200 + cc * 8) = kreg[i]; }
; #pragma unroll
;         for (int i = 0; i < 2; ++i) { const int p = tid + 512 * i, r = p >> 3, cc = p & 7; *(LAS u32x4*)(Vs + r * 72 + cc * 8) = vreg[i]; }
;         __syncthreads();
;         if (t + 1 < ntile) AT_LOAD(kt + 1)
.LBB0_2236:
	s_or_b64 exec, exec, s[38:39]
	s_waitcnt lgkmcnt(0)
	s_barrier
	v_xor_b32_e32 v182, 0x10000, v182
	v_xor_b32_e32 v183, 0x10000, v183
	v_xor_b32_e32 v184, 0x10000, v184
	v_xor_b32_e32 v185, 0x10000, v185
	v_xor_b32_e32 v186, 0x10000, v186
	v_xor_b32_e32 v187, 0x10000, v187
	v_xor_b32_e32 v188, 0x10000, v188
	v_xor_b32_e32 v189, 0x10000, v189
	v_xor_b32_e32 v190, 0x10000, v190
	v_cmp_eq_u32_e32 vcc, s45, v179
	v_lshl_add_u64 v[166:167], v[166:167], 0, s[60:61]
	v_lshl_add_u64 v[168:169], v[168:169], 0, s[60:61]
	v_lshl_add_u64 v[170:171], v[170:171], 0, s[14:15]
	v_lshl_add_u64 v[172:173], v[172:173], 0, s[14:15]
	v_lshl_add_u64 v[174:175], v[174:175], 0, s[14:15]
	s_or_b64 s[36:37], vcc, s[36:37]
	s_mov_b32 s46, s45
	s_andn2_b64 exec, exec, s[36:37]
	s_cbranch_execz .LBB0_2244
	s_branch .LBB0_2237
.Lattn_pre:
	s_waitcnt vmcnt(0)
	ds_write_b128 v182, v[130:133]
	ds_write_b128 v183, v[122:125]
	ds_write_b128 v184, v[126:129]
	ds_write_b128 v185, v[110:113] offset:25600
	ds_write_b128 v186, v[114:117] offset:25600
	v_xor_b32_e32 v182, 0x10000, v182
	v_xor_b32_e32 v183, 0x10000, v183
	v_xor_b32_e32 v184, 0x10000, v184
	v_xor_b32_e32 v185, 0x10000, v185
	v_xor_b32_e32 v186, 0x10000, v186
	s_waitcnt lgkmcnt(0)
	v_cmp_lt_i32_e32 vcc, 1, v179
	s_and_saveexec_b64 s[38:39], vcc
	s_cbranch_execz .Lattn_pre2
	v_lshl_add_u64 v[20:21], s[2:3], 0, v[174:175]
	v_lshl_add_u64 v[110:111], s[2:3], 0, v[172:173]
	global_load_dwordx4 v[130:133], v[20:21], off
	global_load_dwordx4 v[122:125], v[110:111], off
	v_lshl_add_u64 v[20:21], s[2:3], 0, v[170:171]
	v_lshl_add_u64 v[110:111], s[2:3], 0, v[168:169]
	global_load_dwordx4 v[126:129], v[20:21], off
	s_nop 0
	global_load_dwordx4 v[110:113], v[110:111], off
	v_lshl_add_u64 v[20:21], s[2:3], 0, v[166:167]
	global_load_dwordx4 v[114:117], v[20:21], off
.Lattn_pre2:
	s_or_b64 exec, exec, s[38:39]
	v_lshl_add_u64 v[166:167], v[166:167], 0, s[60:61]
	v_lshl_add_u64 v[168:169], v[168:169], 0, s[60:61]
	v_lshl_add_u64 v[170:171], v[170:171], 0, s[14:15]
	v_lshl_add_u64 v[172:173], v[172:173], 0, s[14:15]
	v_lshl_add_u64 v[174:175], v[174:175], 0, s[14:15]
	s_barrier
.LBB0_2237:
	s_add_i32 s45, s46, 1
	v_cmp_lt_i32_e32 vcc, s45, v179
	s_and_saveexec_b64 s[38:39], vcc
	s_cbranch_execz .LBB0_2239
	s_waitcnt vmcnt(0)
	ds_write_b128 v182, v[130:133]
	ds_write_b128 v183, v[122:125]
	ds_write_b128 v184, v[126:129]
	ds_write_b128 v185, v[110:113] offset:25600
	ds_write_b128 v186, v[114:117] offset:25600
	v_add_u32_e32 v18, -1, v179
	s_waitcnt lgkmcnt(0)
	v_cmp_lt_i32_e32 vcc, s45, v18
	s_and_b64 exec, exec, vcc
	s_cbranch_execz .LBB0_2239
	v_lshl_add_u64 v[20:21], s[2:3], 0, v[174:175]
	v_lshl_add_u64 v[110:111], s[2:3], 0, v[172:173]
	global_load_dwordx4 v[130:133], v[20:21], off
	global_load_dwordx4 v[122:125], v[110:111], off
	v_lshl_add_u64 v[20:21], s[2:3], 0, v[170:171]
	v_lshl_add_u64 v[110:111], s[2:3], 0, v[168:169]
	global_load_dwordx4 v[126:129], v[20:21], off
	s_nop 0
	global_load_dwordx4 v[110:113], v[110:111], off
	v_lshl_add_u64 v[20:21], s[2:3], 0, v[166:167]
	global_load_dwordx4 v[114:117], v[20:21], off
